# P10 epilogue: each lane loads two full rows of norm partials (8 loads instead of 32 redundant ones), sums them in the original order and the four lane quarters exchange the row sums by permlane swaps
# speedup vs baseline: 1.0039x; 1.0039x over previous
.LBB0_1363:
	s_lshl_b32 s1, s26, 8
	v_add_u32_e32 v148, s1, v1
	v_ashrrev_i32_e32 v149, 31, v148
	v_lshlrev_b64 v[146:147], 6, v[148:149]
	v_lshl_add_u64 v[146:147], s[12:13], 0, v[146:147]
	v_bfe_u32 v216, v0, 4, 2
	v_lshlrev_b32_e32 v216, 10, v216
	v_mov_b32_e32 v217, 0
	v_lshl_add_u64 v[246:247], v[146:147], 0, v[216:217]
	v_mov_b32_e32 v216, 0x2000
	v_lshl_add_u64 v[248:249], v[246:247], 0, v[216:217]
	global_load_dwordx4 v[184:187], v[246:247], off
	global_load_dwordx4 v[188:191], v[246:247], off offset:16
	global_load_dwordx4 v[192:195], v[246:247], off offset:32
	global_load_dwordx4 v[196:199], v[246:247], off offset:48
	global_load_dwordx4 v[200:203], v[248:249], off
	global_load_dwordx4 v[204:207], v[248:249], off offset:16
	global_load_dwordx4 v[208:211], v[248:249], off offset:32
	global_load_dwordx4 v[212:215], v[248:249], off offset:48
	s_waitcnt vmcnt(0)
	v_pk_add_f32 v[218:219], v[186:187], v[190:191]
	v_pk_add_f32 v[220:221], v[184:185], v[188:189]
	v_pk_add_f32 v[222:223], v[194:195], v[198:199]
	v_pk_add_f32 v[224:225], v[192:193], v[196:197]
	v_pk_add_f32 v[218:219], v[218:219], v[222:223]
	v_pk_add_f32 v[220:221], v[220:221], v[224:225]
	s_nop 0
	v_pk_mov_b32 v[222:223], v[220:221], v[218:219] op_sel:[1,0]
	v_mov_b32_e32 v221, v219
	v_pk_add_f32 v[220:221], v[222:223], v[220:221]
	s_nop 0
	v_add_f32_e32 v226, v220, v221
	v_mov_b32_e32 v227, v226
	s_nop 1
	v_permlane16_swap_b32_e32 v226, v227
	v_mov_b32_e32 v228, v226
	v_mov_b32_e32 v229, v227
	s_nop 1
	v_permlane32_swap_b32_e32 v226, v228
	v_permlane32_swap_b32_e32 v227, v229
	v_pk_add_f32 v[218:219], v[202:203], v[206:207]
	v_pk_add_f32 v[220:221], v[200:201], v[204:205]
	v_pk_add_f32 v[222:223], v[210:211], v[214:215]
	v_pk_add_f32 v[224:225], v[208:209], v[212:213]
	v_pk_add_f32 v[218:219], v[218:219], v[222:223]
	v_pk_add_f32 v[220:221], v[220:221], v[224:225]
	s_nop 0
	v_pk_mov_b32 v[222:223], v[220:221], v[218:219] op_sel:[1,0]
	v_mov_b32_e32 v221, v219
	v_pk_add_f32 v[220:221], v[222:223], v[220:221]
	s_nop 0
	v_add_f32_e32 v230, v220, v221
	v_mov_b32_e32 v231, v230
	s_nop 1
	v_permlane16_swap_b32_e32 v230, v231
	v_mov_b32_e32 v232, v230
	v_mov_b32_e32 v233, v231
	s_nop 1
	v_permlane32_swap_b32_e32 v230, v232
	v_permlane32_swap_b32_e32 v231, v233
	v_mov_b32_e32 v181, v116
	v_mov_b32_e32 v116, v125
	v_mov_b32_e32 v178, v126
	v_mov_b32_e32 v179, v118
	v_mov_b32_e32 v118, v127
	v_mov_b32_e32 v126, v128
	v_mov_b32_e32 v127, v120
	v_mov_b32_e32 v120, v129
	v_mov_b32_e32 v128, v122
	v_mov_b32_e32 v129, v114
	v_mov_b32_e32 v114, v123
	v_mov_b32_e32 v180, v124
	v_lshl_or_b32 v176, s0, 7, v154
	v_mov_b64_e32 v[146:147], s[10:11]
	v_ashrrev_i32_e32 v177, 31, v176
	v_add_u32_e32 v182, s1, v151
	v_mad_i64_i32 v[124:125], s[2:3], v148, s52, v[146:147]
	v_lshlrev_b64 v[122:123], 1, v[176:177]
	v_ashrrev_i32_e32 v183, 31, v182
	v_lshl_add_u64 v[124:125], v[124:125], 0, v[122:123]
	s_andn2_b64 vcc, exec, s[4:5]
	s_mov_b64 s[4:5], -1
	s_nop 0
	v_lshlrev_b64 v[162:163], 6, v[182:183]
	v_mov_b32_e32 v149, v226
	v_fmamk_f32 v149, v149, 0x3a800000, v158
	v_rsq_f32_e32 v160, v149
	v_lshl_add_u64 v[162:163], s[12:13], 0, v[162:163]
	v_pk_mul_f32 v[116:117], v[116:117], v[160:161] op_sel_hi:[1,0]
	v_pk_mul_f32 v[164:165], v[178:179], v[160:161] op_sel_hi:[1,0]
	v_pk_mul_f32 v[118:119], v[118:119], v[160:161] op_sel_hi:[1,0]
	v_pk_mul_f32 v[126:127], v[126:127], v[160:161] op_sel_hi:[1,0]
	v_pk_mul_f32 v[120:121], v[120:121], v[160:161] op_sel_hi:[1,0]
	v_pk_mul_f32 v[128:129], v[128:129], v[160:161] op_sel_hi:[1,0]
	v_pk_mul_f32 v[114:115], v[114:115], v[160:161] op_sel_hi:[1,0]
	v_pk_mul_f32 v[166:167], v[180:181], v[160:161] op_sel_hi:[1,0]
	v_mul_f32_e32 v171, 0xbfb8aa3b, v117
	v_mul_f32_e32 v149, 0xbfb8aa3b, v165
	v_mul_f32_e32 v159, 0xbfb8aa3b, v119
	v_mul_f32_e32 v160, 0xbfb8aa3b, v127
	v_mul_f32_e32 v161, 0xbfb8aa3b, v121
	v_mul_f32_e32 v168, 0xbfb8aa3b, v129
	v_mul_f32_e32 v169, 0xbfb8aa3b, v115
	v_mul_f32_e32 v170, 0xbfb8aa3b, v167
	v_exp_f32_e32 v171, v171
	v_exp_f32_e32 v149, v149
	v_exp_f32_e32 v159, v159
	v_exp_f32_e32 v160, v160
	v_exp_f32_e32 v161, v161
	v_exp_f32_e32 v168, v168
	v_exp_f32_e32 v169, v169
	v_exp_f32_e32 v170, v170
	v_add_f32_e32 v171, 1.0, v171
	v_add_f32_e32 v149, 1.0, v149
	v_add_f32_e32 v159, 1.0, v159
	v_add_f32_e32 v160, 1.0, v160
	v_add_f32_e32 v161, 1.0, v161
	v_add_f32_e32 v168, 1.0, v168
	v_add_f32_e32 v169, 1.0, v169
	v_add_f32_e32 v170, 1.0, v170
	v_rcp_f32_e32 v171, v171
	v_rcp_f32_e32 v149, v149
	v_rcp_f32_e32 v159, v159
	v_rcp_f32_e32 v160, v160
	v_rcp_f32_e32 v161, v161
	v_rcp_f32_e32 v168, v168
	v_rcp_f32_e32 v169, v169
	v_rcp_f32_e32 v170, v170
	v_mul_f32_e32 v117, v117, v171
	v_mul_f32_e32 v149, v165, v149
	v_mul_f32_e32 v119, v119, v159
	v_mul_f32_e32 v127, v127, v160
	v_mul_f32_e32 v121, v121, v161
	v_mul_f32_e32 v129, v129, v168
	v_mul_f32_e32 v115, v115, v169
	v_mul_f32_e32 v159, v167, v170
	v_mul_f32_e32 v117, v116, v117
	v_mul_f32_e32 v149, v164, v149
	v_mul_f32_e32 v118, v118, v119
	v_mul_f32_e32 v119, v126, v127
	v_mul_f32_e32 v120, v120, v121
	v_mul_f32_e32 v121, v128, v129
	v_mul_f32_e32 v126, v114, v115
	v_mul_f32_e32 v127, v166, v159
	v_cvt_pk_bf16_f32 v114, v149, v118
	v_cvt_pk_bf16_f32 v115, v119, v120
	v_cvt_pk_bf16_f32 v116, v121, v126
	v_cvt_pk_bf16_f32 v117, v127, v117
	global_store_dwordx4 v[124:125], v[114:117], off
	s_nop 0
	s_nop 0
	v_mov_b32_e32 v129, v102
	v_mov_b32_e32 v102, v111
	v_mov_b32_e32 v111, v104
	v_mov_b32_e32 v104, v113
	v_mov_b32_e32 v113, v98
	v_mov_b32_e32 v98, v107
	v_mov_b32_e32 v107, v100
	v_mov_b32_e32 v100, v109
	v_mov_b32_e32 v128, v110
	v_mov_b32_e32 v110, v112
	v_mov_b32_e32 v112, v106
	v_mov_b32_e32 v106, v108
	v_add_u32_e32 v164, s1, v152
	v_mad_i64_i32 v[108:109], s[2:3], v182, s52, v[146:147]
	v_ashrrev_i32_e32 v165, 31, v164
	v_lshl_add_u64 v[108:109], v[108:109], 0, v[122:123]
	s_nop 0
	v_lshlrev_b64 v[116:117], 6, v[164:165]
	v_mov_b32_e32 v114, v227
	v_fmamk_f32 v114, v114, 0x3a800000, v158
	v_rsq_f32_e32 v114, v114
	v_lshl_add_u64 v[116:117], s[12:13], 0, v[116:117]
	v_pk_mul_f32 v[100:101], v[100:101], v[114:115] op_sel_hi:[1,0]
	v_pk_mul_f32 v[118:119], v[128:129], v[114:115] op_sel_hi:[1,0]
	v_pk_mul_f32 v[102:103], v[102:103], v[114:115] op_sel_hi:[1,0]
	v_pk_mul_f32 v[110:111], v[110:111], v[114:115] op_sel_hi:[1,0]
	v_pk_mul_f32 v[104:105], v[104:105], v[114:115] op_sel_hi:[1,0]
	v_pk_mul_f32 v[112:113], v[112:113], v[114:115] op_sel_hi:[1,0]
	v_pk_mul_f32 v[98:99], v[98:99], v[114:115] op_sel_hi:[1,0]
	v_pk_mul_f32 v[106:107], v[106:107], v[114:115] op_sel_hi:[1,0]
	v_mul_f32_e32 v127, 0xbfb8aa3b, v101
	v_mul_f32_e32 v114, 0xbfb8aa3b, v119
	v_mul_f32_e32 v115, 0xbfb8aa3b, v103
	v_mul_f32_e32 v120, 0xbfb8aa3b, v111
	v_mul_f32_e32 v121, 0xbfb8aa3b, v105
	v_mul_f32_e32 v124, 0xbfb8aa3b, v113
	v_mul_f32_e32 v125, 0xbfb8aa3b, v99
	v_mul_f32_e32 v126, 0xbfb8aa3b, v107
	v_exp_f32_e32 v127, v127
	v_exp_f32_e32 v114, v114
	v_exp_f32_e32 v115, v115
	v_exp_f32_e32 v120, v120
	v_exp_f32_e32 v121, v121
	v_exp_f32_e32 v124, v124
	v_exp_f32_e32 v125, v125
	v_exp_f32_e32 v126, v126
	v_add_f32_e32 v127, 1.0, v127
	v_add_f32_e32 v114, 1.0, v114
	v_add_f32_e32 v115, 1.0, v115
	v_add_f32_e32 v120, 1.0, v120
	v_add_f32_e32 v121, 1.0, v121
	v_add_f32_e32 v124, 1.0, v124
	v_add_f32_e32 v125, 1.0, v125
	v_add_f32_e32 v126, 1.0, v126
	v_rcp_f32_e32 v127, v127
	v_rcp_f32_e32 v114, v114
	v_rcp_f32_e32 v115, v115
	v_rcp_f32_e32 v120, v120
	v_rcp_f32_e32 v121, v121
	v_rcp_f32_e32 v124, v124
	v_rcp_f32_e32 v125, v125
	v_rcp_f32_e32 v126, v126
	v_mul_f32_e32 v101, v101, v127
	v_mul_f32_e32 v114, v119, v114
	v_mul_f32_e32 v103, v103, v115
	v_mul_f32_e32 v111, v111, v120
	v_mul_f32_e32 v105, v105, v121
	v_mul_f32_e32 v113, v113, v124
	v_mul_f32_e32 v99, v99, v125
	v_mul_f32_e32 v107, v107, v126
	v_mul_f32_e32 v101, v100, v101
	v_mul_f32_e32 v114, v118, v114
	v_mul_f32_e32 v102, v102, v103
	v_mul_f32_e32 v103, v110, v111
	v_mul_f32_e32 v104, v104, v105
	v_mul_f32_e32 v105, v112, v113
	v_mul_f32_e32 v110, v98, v99
	v_mul_f32_e32 v106, v106, v107
	v_cvt_pk_bf16_f32 v98, v114, v102
	v_cvt_pk_bf16_f32 v99, v103, v104
	v_cvt_pk_bf16_f32 v100, v105, v110
	v_cvt_pk_bf16_f32 v101, v106, v101
	global_store_dwordx4 v[108:109], v[98:101], off
	s_nop 0
	v_mov_b32_e32 v115, v86
	v_mov_b32_e32 v86, v95
	v_mov_b32_e32 v95, v88
	v_mov_b32_e32 v88, v97
	v_mov_b32_e32 v97, v82
	v_mov_b32_e32 v82, v91
	v_mov_b32_e32 v91, v84
	v_mov_b32_e32 v84, v93
	v_mov_b32_e32 v114, v94
	v_mov_b32_e32 v94, v96
	v_mov_b32_e32 v96, v90
	v_mov_b32_e32 v90, v92
	v_add_u32_e32 v116, s1, v153
	v_mad_i64_i32 v[92:93], s[0:1], v164, s52, v[146:147]
	v_ashrrev_i32_e32 v117, 31, v116
	v_lshl_add_u64 v[92:93], v[92:93], 0, v[122:123]
	s_nop 0
	v_lshlrev_b64 v[100:101], 6, v[116:117]
	v_mov_b32_e32 v98, v228
	v_fmamk_f32 v98, v98, 0x3a800000, v158
	v_rsq_f32_e32 v98, v98
	v_lshl_add_u64 v[100:101], s[12:13], 0, v[100:101]
	v_pk_mul_f32 v[84:85], v[84:85], v[98:99] op_sel_hi:[1,0]
	v_pk_mul_f32 v[102:103], v[114:115], v[98:99] op_sel_hi:[1,0]
	v_pk_mul_f32 v[86:87], v[86:87], v[98:99] op_sel_hi:[1,0]
	v_pk_mul_f32 v[94:95], v[94:95], v[98:99] op_sel_hi:[1,0]
	v_pk_mul_f32 v[88:89], v[88:89], v[98:99] op_sel_hi:[1,0]
	v_pk_mul_f32 v[96:97], v[96:97], v[98:99] op_sel_hi:[1,0]
	v_pk_mul_f32 v[82:83], v[82:83], v[98:99] op_sel_hi:[1,0]
	v_pk_mul_f32 v[90:91], v[90:91], v[98:99] op_sel_hi:[1,0]
	v_mul_f32_e32 v109, 0xbfb8aa3b, v85
	v_mul_f32_e32 v98, 0xbfb8aa3b, v103
	v_mul_f32_e32 v99, 0xbfb8aa3b, v87
	v_mul_f32_e32 v104, 0xbfb8aa3b, v95
	v_mul_f32_e32 v105, 0xbfb8aa3b, v89
	v_mul_f32_e32 v106, 0xbfb8aa3b, v97
	v_mul_f32_e32 v107, 0xbfb8aa3b, v83
	v_mul_f32_e32 v108, 0xbfb8aa3b, v91
	v_exp_f32_e32 v109, v109
	v_exp_f32_e32 v98, v98
	v_exp_f32_e32 v99, v99
	v_exp_f32_e32 v104, v104
	v_exp_f32_e32 v105, v105
	v_exp_f32_e32 v106, v106
	v_exp_f32_e32 v107, v107
	v_exp_f32_e32 v108, v108
	v_add_f32_e32 v109, 1.0, v109
	v_add_f32_e32 v98, 1.0, v98
	v_add_f32_e32 v99, 1.0, v99
	v_add_f32_e32 v104, 1.0, v104
	v_add_f32_e32 v105, 1.0, v105
	v_add_f32_e32 v106, 1.0, v106
	v_add_f32_e32 v107, 1.0, v107
	v_add_f32_e32 v108, 1.0, v108
	v_rcp_f32_e32 v109, v109
	v_rcp_f32_e32 v98, v98
	v_rcp_f32_e32 v99, v99
	v_rcp_f32_e32 v104, v104
	v_rcp_f32_e32 v105, v105
	v_rcp_f32_e32 v106, v106
	v_rcp_f32_e32 v107, v107
	v_rcp_f32_e32 v108, v108
	v_mul_f32_e32 v85, v85, v109
	v_mul_f32_e32 v98, v103, v98
	v_mul_f32_e32 v87, v87, v99
	v_mul_f32_e32 v95, v95, v104
	v_mul_f32_e32 v89, v89, v105
	v_mul_f32_e32 v97, v97, v106
	v_mul_f32_e32 v83, v83, v107
	v_mul_f32_e32 v91, v91, v108
	v_mul_f32_e32 v85, v84, v85
	v_mul_f32_e32 v98, v102, v98
	v_mul_f32_e32 v86, v86, v87
	v_mul_f32_e32 v87, v94, v95
	v_mul_f32_e32 v88, v88, v89
	v_mul_f32_e32 v89, v96, v97
	v_mul_f32_e32 v94, v82, v83
	v_mul_f32_e32 v90, v90, v91
	v_cvt_pk_bf16_f32 v82, v98, v86
	v_cvt_pk_bf16_f32 v83, v87, v88
	v_cvt_pk_bf16_f32 v84, v89, v94
	v_cvt_pk_bf16_f32 v85, v90, v85
	global_store_dwordx4 v[92:93], v[82:85], off
	s_nop 0
	v_mov_b32_e32 v99, v70
	v_mov_b32_e32 v70, v79
	v_mov_b32_e32 v79, v72
	v_mov_b32_e32 v72, v81
	v_mov_b32_e32 v81, v66
	v_mov_b32_e32 v66, v75
	v_mov_b32_e32 v75, v68
	v_mov_b32_e32 v68, v77
	v_mov_b32_e32 v98, v78
	v_mov_b32_e32 v78, v80
	v_mov_b32_e32 v80, v74
	v_mov_b32_e32 v74, v76
	v_add_u32_e32 v100, 0x80, v148
	v_mad_i64_i32 v[76:77], s[0:1], v116, s52, v[146:147]
	v_ashrrev_i32_e32 v101, 31, v100
	v_lshl_add_u64 v[76:77], v[76:77], 0, v[122:123]
	s_nop 0
	v_lshlrev_b64 v[84:85], 6, v[100:101]
	v_mov_b32_e32 v82, v229
	v_fmamk_f32 v82, v82, 0x3a800000, v158
	v_rsq_f32_e32 v82, v82
	v_lshl_add_u64 v[84:85], s[12:13], 0, v[84:85]
	v_pk_mul_f32 v[68:69], v[68:69], v[82:83] op_sel_hi:[1,0]
	v_pk_mul_f32 v[86:87], v[98:99], v[82:83] op_sel_hi:[1,0]
	v_pk_mul_f32 v[70:71], v[70:71], v[82:83] op_sel_hi:[1,0]
	v_pk_mul_f32 v[78:79], v[78:79], v[82:83] op_sel_hi:[1,0]
	v_pk_mul_f32 v[72:73], v[72:73], v[82:83] op_sel_hi:[1,0]
	v_pk_mul_f32 v[80:81], v[80:81], v[82:83] op_sel_hi:[1,0]
	v_pk_mul_f32 v[66:67], v[66:67], v[82:83] op_sel_hi:[1,0]
	v_pk_mul_f32 v[74:75], v[74:75], v[82:83] op_sel_hi:[1,0]
	v_mul_f32_e32 v93, 0xbfb8aa3b, v69
	v_mul_f32_e32 v82, 0xbfb8aa3b, v87
	v_mul_f32_e32 v83, 0xbfb8aa3b, v71
	v_mul_f32_e32 v88, 0xbfb8aa3b, v79
	v_mul_f32_e32 v89, 0xbfb8aa3b, v73
	v_mul_f32_e32 v90, 0xbfb8aa3b, v81
	v_mul_f32_e32 v91, 0xbfb8aa3b, v67
	v_mul_f32_e32 v92, 0xbfb8aa3b, v75
	v_exp_f32_e32 v93, v93
	v_exp_f32_e32 v82, v82
	v_exp_f32_e32 v83, v83
	v_exp_f32_e32 v88, v88
	v_exp_f32_e32 v89, v89
	v_exp_f32_e32 v90, v90
	v_exp_f32_e32 v91, v91
	v_exp_f32_e32 v92, v92
	v_add_f32_e32 v93, 1.0, v93
	v_add_f32_e32 v82, 1.0, v82
	v_add_f32_e32 v83, 1.0, v83
	v_add_f32_e32 v88, 1.0, v88
	v_add_f32_e32 v89, 1.0, v89
	v_add_f32_e32 v90, 1.0, v90
	v_add_f32_e32 v91, 1.0, v91
	v_add_f32_e32 v92, 1.0, v92
	v_rcp_f32_e32 v93, v93
	v_rcp_f32_e32 v82, v82
	v_rcp_f32_e32 v83, v83
	v_rcp_f32_e32 v88, v88
	v_rcp_f32_e32 v89, v89
	v_rcp_f32_e32 v90, v90
	v_rcp_f32_e32 v91, v91
	v_rcp_f32_e32 v92, v92
	v_mul_f32_e32 v69, v69, v93
	v_mul_f32_e32 v82, v87, v82
	v_mul_f32_e32 v71, v71, v83
	v_mul_f32_e32 v79, v79, v88
	v_mul_f32_e32 v73, v73, v89
	v_mul_f32_e32 v81, v81, v90
	v_mul_f32_e32 v67, v67, v91
	v_mul_f32_e32 v75, v75, v92
	v_mul_f32_e32 v69, v68, v69
	v_mul_f32_e32 v82, v86, v82
	v_mul_f32_e32 v70, v70, v71
	v_mul_f32_e32 v71, v78, v79
	v_mul_f32_e32 v72, v72, v73
	v_mul_f32_e32 v73, v80, v81
	v_mul_f32_e32 v78, v66, v67
	v_mul_f32_e32 v74, v74, v75
	v_cvt_pk_bf16_f32 v66, v82, v70
	v_cvt_pk_bf16_f32 v67, v71, v72
	v_cvt_pk_bf16_f32 v68, v73, v78
	v_cvt_pk_bf16_f32 v69, v74, v69
	global_store_dwordx4 v[76:77], v[66:69], off
	s_nop 0
	v_mov_b32_e32 v83, v54
	v_mov_b32_e32 v54, v63
	v_mov_b32_e32 v63, v56
	v_mov_b32_e32 v56, v65
	v_mov_b32_e32 v65, v50
	v_mov_b32_e32 v50, v59
	v_mov_b32_e32 v59, v52
	v_mov_b32_e32 v52, v61
	v_mov_b32_e32 v82, v62
	v_mov_b32_e32 v62, v64
	v_mov_b32_e32 v64, v58
	v_mov_b32_e32 v58, v60
	v_add_u32_e32 v84, 0x90, v148
	v_mad_i64_i32 v[60:61], s[0:1], v100, s52, v[146:147]
	v_ashrrev_i32_e32 v85, 31, v84
	v_lshl_add_u64 v[60:61], v[60:61], 0, v[122:123]
	s_nop 0
	v_lshlrev_b64 v[68:69], 6, v[84:85]
	v_mov_b32_e32 v66, v230
	v_fmamk_f32 v66, v66, 0x3a800000, v158
	v_rsq_f32_e32 v66, v66
	v_lshl_add_u64 v[68:69], s[12:13], 0, v[68:69]
	v_pk_mul_f32 v[52:53], v[52:53], v[66:67] op_sel_hi:[1,0]
	v_pk_mul_f32 v[70:71], v[82:83], v[66:67] op_sel_hi:[1,0]
	v_pk_mul_f32 v[54:55], v[54:55], v[66:67] op_sel_hi:[1,0]
	v_pk_mul_f32 v[62:63], v[62:63], v[66:67] op_sel_hi:[1,0]
	v_pk_mul_f32 v[56:57], v[56:57], v[66:67] op_sel_hi:[1,0]
	v_pk_mul_f32 v[64:65], v[64:65], v[66:67] op_sel_hi:[1,0]
	v_pk_mul_f32 v[50:51], v[50:51], v[66:67] op_sel_hi:[1,0]
	v_pk_mul_f32 v[58:59], v[58:59], v[66:67] op_sel_hi:[1,0]
	v_mul_f32_e32 v77, 0xbfb8aa3b, v53
	v_mul_f32_e32 v66, 0xbfb8aa3b, v71
	v_mul_f32_e32 v67, 0xbfb8aa3b, v55
	v_mul_f32_e32 v72, 0xbfb8aa3b, v63
	v_mul_f32_e32 v73, 0xbfb8aa3b, v57
	v_mul_f32_e32 v74, 0xbfb8aa3b, v65
	v_mul_f32_e32 v75, 0xbfb8aa3b, v51
	v_mul_f32_e32 v76, 0xbfb8aa3b, v59
	v_exp_f32_e32 v77, v77
	v_exp_f32_e32 v66, v66
	v_exp_f32_e32 v67, v67
	v_exp_f32_e32 v72, v72
	v_exp_f32_e32 v73, v73
	v_exp_f32_e32 v74, v74
	v_exp_f32_e32 v75, v75
	v_exp_f32_e32 v76, v76
	v_add_f32_e32 v77, 1.0, v77
	v_add_f32_e32 v66, 1.0, v66
	v_add_f32_e32 v67, 1.0, v67
	v_add_f32_e32 v72, 1.0, v72
	v_add_f32_e32 v73, 1.0, v73
	v_add_f32_e32 v74, 1.0, v74
	v_add_f32_e32 v75, 1.0, v75
	v_add_f32_e32 v76, 1.0, v76
	v_rcp_f32_e32 v77, v77
	v_rcp_f32_e32 v66, v66
	v_rcp_f32_e32 v67, v67
	v_rcp_f32_e32 v72, v72
	v_rcp_f32_e32 v73, v73
	v_rcp_f32_e32 v74, v74
	v_rcp_f32_e32 v75, v75
	v_rcp_f32_e32 v76, v76
	v_mul_f32_e32 v53, v53, v77
	v_mul_f32_e32 v66, v71, v66
	v_mul_f32_e32 v55, v55, v67
	v_mul_f32_e32 v63, v63, v72
	v_mul_f32_e32 v57, v57, v73
	v_mul_f32_e32 v65, v65, v74
	v_mul_f32_e32 v51, v51, v75
	v_mul_f32_e32 v59, v59, v76
	v_mul_f32_e32 v53, v52, v53
	v_mul_f32_e32 v66, v70, v66
	v_mul_f32_e32 v54, v54, v55
	v_mul_f32_e32 v55, v62, v63
	v_mul_f32_e32 v56, v56, v57
	v_mul_f32_e32 v57, v64, v65
	v_mul_f32_e32 v62, v50, v51
	v_mul_f32_e32 v58, v58, v59
	v_cvt_pk_bf16_f32 v50, v66, v54
	v_cvt_pk_bf16_f32 v51, v55, v56
	v_cvt_pk_bf16_f32 v52, v57, v62
	v_cvt_pk_bf16_f32 v53, v58, v53
	global_store_dwordx4 v[60:61], v[50:53], off
	s_nop 0
	v_mov_b32_e32 v67, v38
	v_mov_b32_e32 v38, v47
	v_mov_b32_e32 v47, v40
	v_mov_b32_e32 v40, v49
	v_mov_b32_e32 v49, v34
	v_mov_b32_e32 v34, v43
	v_mov_b32_e32 v43, v36
	v_mov_b32_e32 v36, v45
	v_mov_b32_e32 v66, v46
	v_mov_b32_e32 v46, v48
	v_mov_b32_e32 v48, v42
	v_mov_b32_e32 v42, v44
	v_add_u32_e32 v68, 0xa0, v148
	v_mad_i64_i32 v[44:45], s[0:1], v84, s52, v[146:147]
	v_ashrrev_i32_e32 v69, 31, v68
	v_lshl_add_u64 v[44:45], v[44:45], 0, v[122:123]
	s_nop 0
	v_lshlrev_b64 v[52:53], 6, v[68:69]
	v_mov_b32_e32 v50, v231
	v_fmamk_f32 v50, v50, 0x3a800000, v158
	v_rsq_f32_e32 v50, v50
	v_lshl_add_u64 v[52:53], s[12:13], 0, v[52:53]
	v_pk_mul_f32 v[36:37], v[36:37], v[50:51] op_sel_hi:[1,0]
	v_pk_mul_f32 v[54:55], v[66:67], v[50:51] op_sel_hi:[1,0]
	v_pk_mul_f32 v[38:39], v[38:39], v[50:51] op_sel_hi:[1,0]
	v_pk_mul_f32 v[46:47], v[46:47], v[50:51] op_sel_hi:[1,0]
	v_pk_mul_f32 v[40:41], v[40:41], v[50:51] op_sel_hi:[1,0]
	v_pk_mul_f32 v[48:49], v[48:49], v[50:51] op_sel_hi:[1,0]
	v_pk_mul_f32 v[34:35], v[34:35], v[50:51] op_sel_hi:[1,0]
	v_pk_mul_f32 v[42:43], v[42:43], v[50:51] op_sel_hi:[1,0]
	v_mul_f32_e32 v61, 0xbfb8aa3b, v37
	v_mul_f32_e32 v50, 0xbfb8aa3b, v55
	v_mul_f32_e32 v51, 0xbfb8aa3b, v39
	v_mul_f32_e32 v56, 0xbfb8aa3b, v47
	v_mul_f32_e32 v57, 0xbfb8aa3b, v41
	v_mul_f32_e32 v58, 0xbfb8aa3b, v49
	v_mul_f32_e32 v59, 0xbfb8aa3b, v35
	v_mul_f32_e32 v60, 0xbfb8aa3b, v43
	v_exp_f32_e32 v61, v61
	v_exp_f32_e32 v50, v50
	v_exp_f32_e32 v51, v51
	v_exp_f32_e32 v56, v56
	v_exp_f32_e32 v57, v57
	v_exp_f32_e32 v58, v58
	v_exp_f32_e32 v59, v59
	v_exp_f32_e32 v60, v60
	v_add_f32_e32 v61, 1.0, v61
	v_add_f32_e32 v50, 1.0, v50
	v_add_f32_e32 v51, 1.0, v51
	v_add_f32_e32 v56, 1.0, v56
	v_add_f32_e32 v57, 1.0, v57
	v_add_f32_e32 v58, 1.0, v58
	v_add_f32_e32 v59, 1.0, v59
	v_add_f32_e32 v60, 1.0, v60
	v_rcp_f32_e32 v61, v61
	v_rcp_f32_e32 v50, v50
	v_rcp_f32_e32 v51, v51
	v_rcp_f32_e32 v56, v56
	v_rcp_f32_e32 v57, v57
	v_rcp_f32_e32 v58, v58
	v_rcp_f32_e32 v59, v59
	v_rcp_f32_e32 v60, v60
	v_mul_f32_e32 v37, v37, v61
	v_mul_f32_e32 v50, v55, v50
	v_mul_f32_e32 v39, v39, v51
	v_mul_f32_e32 v47, v47, v56
	v_mul_f32_e32 v41, v41, v57
	v_mul_f32_e32 v49, v49, v58
	v_mul_f32_e32 v35, v35, v59
	v_mul_f32_e32 v43, v43, v60
	v_mul_f32_e32 v37, v36, v37
	v_mul_f32_e32 v50, v54, v50
	v_mul_f32_e32 v38, v38, v39
	v_mul_f32_e32 v39, v46, v47
	v_mul_f32_e32 v40, v40, v41
	v_mul_f32_e32 v41, v48, v49
	v_mul_f32_e32 v46, v34, v35
	v_mul_f32_e32 v42, v42, v43
	v_cvt_pk_bf16_f32 v34, v50, v38
	v_cvt_pk_bf16_f32 v35, v39, v40
	v_cvt_pk_bf16_f32 v36, v41, v46
	v_cvt_pk_bf16_f32 v37, v42, v37
	global_store_dwordx4 v[44:45], v[34:37], off
	s_nop 0
	v_mov_b32_e32 v51, v22
	v_mov_b32_e32 v22, v31
	v_mov_b32_e32 v31, v24
	v_mov_b32_e32 v24, v33
	v_mov_b32_e32 v33, v18
	v_mov_b32_e32 v18, v27
	v_mov_b32_e32 v27, v20
	v_mov_b32_e32 v20, v29
	v_mov_b32_e32 v50, v30
	v_mov_b32_e32 v30, v32
	v_mov_b32_e32 v32, v26
	v_mov_b32_e32 v26, v28
	v_add_u32_e32 v52, 0xb0, v148
	v_mad_i64_i32 v[28:29], s[0:1], v68, s52, v[146:147]
	v_ashrrev_i32_e32 v53, 31, v52
	v_lshl_add_u64 v[28:29], v[28:29], 0, v[122:123]
	s_nop 0
	v_lshlrev_b64 v[36:37], 6, v[52:53]
	v_mov_b32_e32 v34, v232
	v_fmamk_f32 v34, v34, 0x3a800000, v158
	v_rsq_f32_e32 v34, v34
	v_lshl_add_u64 v[36:37], s[12:13], 0, v[36:37]
	v_pk_mul_f32 v[20:21], v[20:21], v[34:35] op_sel_hi:[1,0]
	v_pk_mul_f32 v[38:39], v[50:51], v[34:35] op_sel_hi:[1,0]
	v_pk_mul_f32 v[22:23], v[22:23], v[34:35] op_sel_hi:[1,0]
	v_pk_mul_f32 v[30:31], v[30:31], v[34:35] op_sel_hi:[1,0]
	v_pk_mul_f32 v[24:25], v[24:25], v[34:35] op_sel_hi:[1,0]
	v_pk_mul_f32 v[32:33], v[32:33], v[34:35] op_sel_hi:[1,0]
	v_pk_mul_f32 v[18:19], v[18:19], v[34:35] op_sel_hi:[1,0]
	v_pk_mul_f32 v[26:27], v[26:27], v[34:35] op_sel_hi:[1,0]
	v_mul_f32_e32 v45, 0xbfb8aa3b, v21
	v_mul_f32_e32 v34, 0xbfb8aa3b, v39
	v_mul_f32_e32 v35, 0xbfb8aa3b, v23
	v_mul_f32_e32 v40, 0xbfb8aa3b, v31
	v_mul_f32_e32 v41, 0xbfb8aa3b, v25
	v_mul_f32_e32 v42, 0xbfb8aa3b, v33
	v_mul_f32_e32 v43, 0xbfb8aa3b, v19
	v_mul_f32_e32 v44, 0xbfb8aa3b, v27
	v_exp_f32_e32 v45, v45
	v_exp_f32_e32 v34, v34
	v_exp_f32_e32 v35, v35
	v_exp_f32_e32 v40, v40
	v_exp_f32_e32 v41, v41
	v_exp_f32_e32 v42, v42
	v_exp_f32_e32 v43, v43
	v_exp_f32_e32 v44, v44
	v_add_f32_e32 v45, 1.0, v45
	v_add_f32_e32 v34, 1.0, v34
	v_add_f32_e32 v35, 1.0, v35
	v_add_f32_e32 v40, 1.0, v40
	v_add_f32_e32 v41, 1.0, v41
	v_add_f32_e32 v42, 1.0, v42
	v_add_f32_e32 v43, 1.0, v43
	v_add_f32_e32 v44, 1.0, v44
	v_rcp_f32_e32 v45, v45
	v_rcp_f32_e32 v34, v34
	v_rcp_f32_e32 v35, v35
	v_rcp_f32_e32 v40, v40
	v_rcp_f32_e32 v41, v41
	v_rcp_f32_e32 v42, v42
	v_rcp_f32_e32 v43, v43
	v_rcp_f32_e32 v44, v44
	v_mul_f32_e32 v21, v21, v45
	v_mul_f32_e32 v34, v39, v34
	v_mul_f32_e32 v23, v23, v35
	v_mul_f32_e32 v31, v31, v40
	v_mul_f32_e32 v25, v25, v41
	v_mul_f32_e32 v33, v33, v42
	v_mul_f32_e32 v19, v19, v43
	v_mul_f32_e32 v27, v27, v44
	v_mul_f32_e32 v21, v20, v21
	v_mul_f32_e32 v34, v38, v34
	v_mul_f32_e32 v22, v22, v23
	v_mul_f32_e32 v23, v30, v31
	v_mul_f32_e32 v24, v24, v25
	v_mul_f32_e32 v25, v32, v33
	v_mul_f32_e32 v30, v18, v19
	v_mul_f32_e32 v26, v26, v27
	v_cvt_pk_bf16_f32 v18, v34, v22
	v_cvt_pk_bf16_f32 v19, v23, v24
	v_cvt_pk_bf16_f32 v20, v25, v30
	v_cvt_pk_bf16_f32 v21, v26, v21
	global_store_dwordx4 v[28:29], v[18:21], off
	s_nop 0
	v_mov_b32_e32 v34, v14
	v_mov_b32_e32 v35, v10
	v_mov_b32_e32 v10, v15
	v_mov_b32_e32 v14, v16
	v_mov_b32_e32 v15, v12
	v_mov_b32_e32 v12, v17
	v_mov_b32_e32 v16, v6
	v_mov_b32_e32 v17, v2
	v_mov_b32_e32 v2, v7
	v_mov_b32_e32 v6, v8
	v_mov_b32_e32 v7, v4
	v_mov_b32_e32 v4, v9
	s_nop 0
	v_mad_i64_i32 v[18:19], s[0:1], v52, s52, v[146:147]
	v_mov_b32_e32 v8, v233
	v_fmamk_f32 v8, v8, 0x3a800000, v158
	v_rsq_f32_e32 v8, v8
	v_lshl_add_u64 v[18:19], v[18:19], 0, v[122:123]
	v_pk_mul_f32 v[4:5], v[4:5], v[8:9] op_sel_hi:[1,0]
	v_pk_mul_f32 v[20:21], v[34:35], v[8:9] op_sel_hi:[1,0]
	v_pk_mul_f32 v[10:11], v[10:11], v[8:9] op_sel_hi:[1,0]
	v_pk_mul_f32 v[14:15], v[14:15], v[8:9] op_sel_hi:[1,0]
	v_pk_mul_f32 v[12:13], v[12:13], v[8:9] op_sel_hi:[1,0]
	v_pk_mul_f32 v[16:17], v[16:17], v[8:9] op_sel_hi:[1,0]
	v_pk_mul_f32 v[2:3], v[2:3], v[8:9] op_sel_hi:[1,0]
	v_pk_mul_f32 v[6:7], v[6:7], v[8:9] op_sel_hi:[1,0]
	v_mul_f32_e32 v27, 0xbfb8aa3b, v5
	v_mul_f32_e32 v8, 0xbfb8aa3b, v21
	v_mul_f32_e32 v9, 0xbfb8aa3b, v11
	v_mul_f32_e32 v22, 0xbfb8aa3b, v15
	v_mul_f32_e32 v23, 0xbfb8aa3b, v13
	v_mul_f32_e32 v24, 0xbfb8aa3b, v17
	v_mul_f32_e32 v25, 0xbfb8aa3b, v3
	v_mul_f32_e32 v26, 0xbfb8aa3b, v7
	v_exp_f32_e32 v27, v27
	v_exp_f32_e32 v8, v8
	v_exp_f32_e32 v9, v9
	v_exp_f32_e32 v22, v22
	v_exp_f32_e32 v23, v23
	v_exp_f32_e32 v24, v24
	v_exp_f32_e32 v25, v25
	v_exp_f32_e32 v26, v26
	v_add_f32_e32 v27, 1.0, v27
	v_add_f32_e32 v8, 1.0, v8
	v_add_f32_e32 v9, 1.0, v9
	v_add_f32_e32 v22, 1.0, v22
	v_add_f32_e32 v23, 1.0, v23
	v_add_f32_e32 v24, 1.0, v24
	v_add_f32_e32 v25, 1.0, v25
	v_add_f32_e32 v26, 1.0, v26
	v_rcp_f32_e32 v27, v27
	v_rcp_f32_e32 v8, v8
	v_rcp_f32_e32 v9, v9
	v_rcp_f32_e32 v22, v22
	v_rcp_f32_e32 v23, v23
	v_rcp_f32_e32 v24, v24
	v_rcp_f32_e32 v25, v25
	v_rcp_f32_e32 v26, v26
	v_mul_f32_e32 v5, v5, v27
	v_mul_f32_e32 v8, v21, v8
	v_mul_f32_e32 v9, v11, v9
	v_mul_f32_e32 v11, v15, v22
	v_mul_f32_e32 v13, v13, v23
	v_mul_f32_e32 v15, v17, v24
	v_mul_f32_e32 v3, v3, v25
	v_mul_f32_e32 v7, v7, v26
	v_mul_f32_e32 v5, v4, v5
	v_mul_f32_e32 v8, v20, v8
	v_mul_f32_e32 v9, v10, v9
	v_mul_f32_e32 v10, v14, v11
	v_mul_f32_e32 v11, v12, v13
	v_mul_f32_e32 v12, v16, v15
	v_mul_f32_e32 v13, v2, v3
	v_mul_f32_e32 v6, v6, v7
	v_cvt_pk_bf16_f32 v2, v8, v9
	v_cvt_pk_bf16_f32 v3, v10, v11
	v_cvt_pk_bf16_f32 v4, v12, v13
	v_cvt_pk_bf16_f32 v5, v6, v5
	global_store_dwordx4 v[18:19], v[2:5], off
	s_cbranch_vccnz .LBB0_1356
	s_andn2_b64 vcc, exec, s[6:7]
	s_cbranch_vccnz .LBB0_1355
	s_barrier
	s_branch .LBB0_1355
